# epilogue de-serialisation phase 7: hoist residual loads of row blocks 1..7 to epilogue top (dead VGPRs), drop per-block vmcnt waits
# baseline (speedup 1.0000x reference)
.LBB0_668:
	v_lshl_add_u32 v164, s72, 8, v166
	v_ashrrev_i32_e32 v165, 31, v164
	s_ashr_i32 s28, s72, 4
	v_lshl_or_b32 v162, s10, 8, v168
	v_lshlrev_b64 v[82:83], 11, v[164:165]
	s_mul_hi_i32 s29, s28, 0x6000
	s_mulk_i32 s28, 0x6000
	v_ashrrev_i32_e32 v163, 31, v162
	v_lshl_add_u64 v[82:83], s[20:21], 0, v[82:83]
	s_add_u32 s28, s46, s28
	v_lshl_add_u64 v[182:183], v[162:163], 1, v[82:83]
	s_addc_u32 s29, s47, s29
	global_load_dwordx4 v[174:177], v[182:183], off
	global_load_dwordx4 v[178:181], v[182:183], off offset:256
	v_add_co_u32_e32 v252, vcc, 0x8000, v182
	v_addc_co_u32_e32 v253, vcc, 0, v183, vcc
	global_load_dwordx4 v[194:197], v[252:253], off
	global_load_dwordx4 v[198:201], v[252:253], off offset:256
	v_add_co_u32_e32 v252, vcc, 0x10000, v182
	v_addc_co_u32_e32 v253, vcc, 0, v183, vcc
	global_load_dwordx4 v[202:205], v[252:253], off
	global_load_dwordx4 v[206:209], v[252:253], off offset:256
	v_add_co_u32_e32 v252, vcc, 0x18000, v182
	v_addc_co_u32_e32 v253, vcc, 0, v183, vcc
	global_load_dwordx4 v[212:215], v[252:253], off
	global_load_dwordx4 v[216:219], v[252:253], off offset:256
	v_add_co_u32_e32 v252, vcc, 0x40000, v182
	v_addc_co_u32_e32 v253, vcc, 0, v183, vcc
	global_load_dwordx4 v[220:223], v[252:253], off
	global_load_dwordx4 v[224:227], v[252:253], off offset:256
	v_add_co_u32_e32 v252, vcc, 0x48000, v182
	v_addc_co_u32_e32 v253, vcc, 0, v183, vcc
	global_load_dwordx4 v[228:231], v[252:253], off
	global_load_dwordx4 v[232:235], v[252:253], off offset:256
	v_add_co_u32_e32 v252, vcc, 0x50000, v182
	v_addc_co_u32_e32 v253, vcc, 0, v183, vcc
	global_load_dwordx4 v[236:239], v[252:253], off
	global_load_dwordx4 v[240:243], v[252:253], off offset:256
	v_add_co_u32_e32 v252, vcc, 0x58000, v182
	v_addc_co_u32_e32 v253, vcc, 0, v183, vcc
	global_load_dwordx4 v[244:247], v[252:253], off
	global_load_dwordx4 v[248:251], v[252:253], off offset:256
	v_lshl_add_u64 v[82:83], v[162:163], 2, s[28:29]
	global_load_dwordx4 v[94:97], v[82:83], off
	global_load_dwordx4 v[90:93], v[82:83], off offset:16
	global_load_dwordx4 v[86:89], v[82:83], off offset:512
	s_nop 0
	global_load_dwordx4 v[82:85], v[82:83], off offset:528
	v_pk_add_f32 v[184:185], v[132:133], 0 op_sel_hi:[1,0]
	v_and_b32_e32 v133, 64, v172
	v_xor_b32_e32 v132, 16, v172
	v_add_u32_e32 v133, 64, v133
	v_pk_add_f32 v[144:145], v[144:145], 0 op_sel_hi:[1,0]
	v_pk_add_f32 v[142:143], v[142:143], 0 op_sel_hi:[1,0]
	v_pk_add_f32 v[140:141], v[140:141], 0 op_sel_hi:[1,0]
	v_pk_add_f32 v[138:139], v[138:139], 0 op_sel_hi:[1,0]
	v_pk_add_f32 v[136:137], v[136:137], 0 op_sel_hi:[1,0]
	v_pk_add_f32 v[134:135], v[134:135], 0 op_sel_hi:[1,0]
	v_pk_add_f32 v[130:131], v[130:131], 0 op_sel_hi:[1,0]
	v_xor_b32_e32 v173, 32, v172
	v_cmp_lt_i32_e32 vcc, v132, v133
	s_lshl_b32 s28, s10, 2
	s_ashr_i32 s29, s28, 31
	v_cndmask_b32_e32 v132, v172, v132, vcc
	v_cmp_lt_i32_e32 vcc, v173, v133
	v_lshlrev_b32_e32 v132, 2, v132
	s_waitcnt vmcnt(0)
	v_lshlrev_b32_e32 v186, 16, v174
	v_and_b32_e32 v187, 0xffff0000, v174
	v_lshlrev_b32_e32 v174, 16, v175
	v_and_b32_e32 v175, 0xffff0000, v175
	v_lshlrev_b32_e32 v188, 16, v176
	v_and_b32_e32 v189, 0xffff0000, v176
	v_lshlrev_b32_e32 v176, 16, v177
	v_and_b32_e32 v177, 0xffff0000, v177
	v_lshlrev_b32_e32 v190, 16, v178
	v_and_b32_e32 v191, 0xffff0000, v178
	v_lshlrev_b32_e32 v178, 16, v179
	v_and_b32_e32 v179, 0xffff0000, v179
	v_lshlrev_b32_e32 v192, 16, v180
	v_and_b32_e32 v193, 0xffff0000, v180
	v_lshlrev_b32_e32 v180, 16, v181
	v_and_b32_e32 v181, 0xffff0000, v181
	v_pk_fma_f32 v[144:145], v[144:145], v[96:97], v[174:175]
	v_pk_fma_f32 v[142:143], v[142:143], v[94:95], v[186:187]
	v_pk_fma_f32 v[140:141], v[140:141], v[92:93], v[176:177]
	v_pk_fma_f32 v[138:139], v[138:139], v[90:91], v[188:189]
	v_pk_fma_f32 v[174:175], v[136:137], v[88:89], v[178:179]
	v_pk_fma_f32 v[176:177], v[134:135], v[86:87], v[190:191]
	v_pk_fma_f32 v[178:179], v[184:185], v[84:85], v[180:181]
	v_pk_fma_f32 v[180:181], v[130:131], v[82:83], v[192:193]
	v_cndmask_b32_e32 v133, v172, v173, vcc
	v_mul_f32_e32 v130, v143, v143
	v_mul_f32_e32 v131, v145, v145
	v_mul_f32_e32 v136, v139, v139
	v_mul_f32_e32 v137, v141, v141
	v_cvt_pk_bf16_f32 v134, v142, v143
	v_cvt_pk_bf16_f32 v135, v144, v145
	v_mul_f32_e32 v143, v177, v177
	v_mul_f32_e32 v145, v175, v175
	v_mul_f32_e32 v173, v181, v181
	v_mul_f32_e32 v184, v179, v179
	v_fmac_f32_e32 v130, v142, v142
	v_fmac_f32_e32 v131, v144, v144
	v_fmac_f32_e32 v136, v138, v138
	v_fmac_f32_e32 v137, v140, v140
	v_fmac_f32_e32 v143, v176, v176
	v_fmac_f32_e32 v145, v174, v174
	v_fmac_f32_e32 v173, v180, v180
	v_fmac_f32_e32 v184, v178, v178
	v_add_f32_e32 v130, v130, v131
	v_add_f32_e32 v131, v136, v137
	v_add_f32_e32 v136, v143, v145
	v_add_f32_e32 v137, v173, v184
	v_add_f32_e32 v130, v130, v131
	v_add_f32_e32 v131, v136, v137
	v_add_f32_e32 v130, v130, v131
	ds_bpermute_b32 v131, v132, v130
	v_lshlrev_b32_e32 v133, 2, v133
	v_cvt_pk_bf16_f32 v136, v138, v139
	v_cvt_pk_bf16_f32 v137, v140, v141
	v_cvt_pk_bf16_f32 v138, v176, v177
	s_waitcnt lgkmcnt(0)
	v_add_f32_e32 v130, v130, v131
	ds_bpermute_b32 v131, v133, v130
	v_cvt_pk_bf16_f32 v139, v174, v175
	v_cvt_pk_bf16_f32 v140, v180, v181
	v_cvt_pk_bf16_f32 v141, v178, v179
	global_store_dwordx4 v[182:183], v[134:137], off
	global_store_dwordx4 v[182:183], v[138:141], off offset:256
	s_and_saveexec_b64 s[30:31], s[0:1]
	s_cbranch_execz .LBB0_670
	v_lshlrev_b64 v[134:135], 6, v[164:165]
	v_lshl_add_u64 v[134:135], s[14:15], 0, v[134:135]
	v_lshl_add_u64 v[134:135], s[28:29], 2, v[134:135]
	s_lshl_b32 s10, s62, 2
	v_lshl_add_u64 v[134:135], v[134:135], 0, s[10:11]
	s_waitcnt lgkmcnt(0)
	v_add_f32_e32 v130, v130, v131
	global_store_dword v[134:135], v130, off
.LBB0_670:
	s_or_b64 exec, exec, s[30:31]
	v_or_b32_e32 v130, 16, v164
	s_waitcnt lgkmcnt(0)
	v_ashrrev_i32_e32 v131, 31, v130
	v_lshlrev_b64 v[134:135], 11, v[130:131]
	v_lshl_add_u64 v[134:135], s[20:21], 0, v[134:135]
	v_lshl_add_u64 v[142:143], v[162:163], 1, v[134:135]
	s_nop 1
	v_pk_mov_b32 v[134:135], v[194:195], v[194:195] op_sel:[0,1]
	v_pk_mov_b32 v[136:137], v[196:197], v[196:197] op_sel:[0,1]
	v_pk_mov_b32 v[138:139], v[198:199], v[198:199] op_sel:[0,1]
	v_pk_mov_b32 v[140:141], v[200:201], v[200:201] op_sel:[0,1]
	v_pk_add_f32 v[128:129], v[128:129], 0 op_sel_hi:[1,0]
	v_pk_add_f32 v[126:127], v[126:127], 0 op_sel_hi:[1,0]
	v_pk_add_f32 v[124:125], v[124:125], 0 op_sel_hi:[1,0]
	v_pk_add_f32 v[122:123], v[122:123], 0 op_sel_hi:[1,0]
	v_pk_add_f32 v[120:121], v[120:121], 0 op_sel_hi:[1,0]
	v_pk_add_f32 v[118:119], v[118:119], 0 op_sel_hi:[1,0]
	v_pk_add_f32 v[116:117], v[116:117], 0 op_sel_hi:[1,0]
	v_pk_add_f32 v[114:115], v[114:115], 0 op_sel_hi:[1,0]
	v_lshlrev_b32_e32 v144, 16, v134
	v_and_b32_e32 v145, 0xffff0000, v134
	v_lshlrev_b32_e32 v134, 16, v135
	v_and_b32_e32 v135, 0xffff0000, v135
	v_lshlrev_b32_e32 v174, 16, v136
	v_and_b32_e32 v175, 0xffff0000, v136
	v_lshlrev_b32_e32 v136, 16, v137
	v_and_b32_e32 v137, 0xffff0000, v137
	v_lshlrev_b32_e32 v176, 16, v138
	v_and_b32_e32 v177, 0xffff0000, v138
	v_lshlrev_b32_e32 v138, 16, v139
	v_and_b32_e32 v139, 0xffff0000, v139
	v_lshlrev_b32_e32 v178, 16, v140
	v_and_b32_e32 v179, 0xffff0000, v140
	v_lshlrev_b32_e32 v140, 16, v141
	v_and_b32_e32 v141, 0xffff0000, v141
	v_pk_fma_f32 v[128:129], v[128:129], v[96:97], v[134:135]
	v_pk_fma_f32 v[126:127], v[126:127], v[94:95], v[144:145]
	v_pk_fma_f32 v[124:125], v[124:125], v[92:93], v[136:137]
	v_pk_fma_f32 v[122:123], v[122:123], v[90:91], v[174:175]
	v_pk_fma_f32 v[120:121], v[120:121], v[88:89], v[138:139]
	v_pk_fma_f32 v[118:119], v[118:119], v[86:87], v[176:177]
	v_pk_fma_f32 v[134:135], v[116:117], v[84:85], v[140:141]
	v_pk_fma_f32 v[136:137], v[114:115], v[82:83], v[178:179]
	v_mul_f32_e32 v116, v127, v127
	v_mul_f32_e32 v117, v129, v129
	v_mul_f32_e32 v138, v123, v123
	v_mul_f32_e32 v139, v125, v125
	v_cvt_pk_bf16_f32 v114, v126, v127
	v_cvt_pk_bf16_f32 v115, v128, v129
	v_mul_f32_e32 v127, v119, v119
	v_mul_f32_e32 v129, v121, v121
	v_mul_f32_e32 v140, v137, v137
	v_mul_f32_e32 v141, v135, v135
	v_fmac_f32_e32 v116, v126, v126
	v_fmac_f32_e32 v117, v128, v128
	v_fmac_f32_e32 v138, v122, v122
	v_fmac_f32_e32 v139, v124, v124
	v_fmac_f32_e32 v127, v118, v118
	v_fmac_f32_e32 v129, v120, v120
	v_fmac_f32_e32 v140, v136, v136
	v_fmac_f32_e32 v141, v134, v134
	v_add_f32_e32 v116, v116, v117
	v_add_f32_e32 v117, v138, v139
	v_add_f32_e32 v126, v127, v129
	v_add_f32_e32 v127, v140, v141
	v_add_f32_e32 v116, v116, v117
	v_add_f32_e32 v117, v126, v127
	v_add_f32_e32 v126, v116, v117
	ds_bpermute_b32 v127, v132, v126
	v_cvt_pk_bf16_f32 v116, v122, v123
	v_cvt_pk_bf16_f32 v117, v124, v125
	global_store_dwordx4 v[142:143], v[114:117], off
	s_waitcnt lgkmcnt(0)
	s_nop 0
	v_add_f32_e32 v114, v126, v127
	ds_bpermute_b32 v115, v133, v114
	v_cvt_pk_bf16_f32 v116, v118, v119
	v_cvt_pk_bf16_f32 v117, v120, v121
	v_cvt_pk_bf16_f32 v118, v136, v137
	v_cvt_pk_bf16_f32 v119, v134, v135
	global_store_dwordx4 v[142:143], v[116:119], off offset:256
	s_and_saveexec_b64 s[30:31], s[0:1]
	s_cbranch_execz .LBB0_672
	v_lshlrev_b64 v[116:117], 6, v[130:131]
	v_lshl_add_u64 v[116:117], s[14:15], 0, v[116:117]
	v_lshl_add_u64 v[116:117], s[28:29], 2, v[116:117]
	s_lshl_b32 s10, s62, 2
	v_lshl_add_u64 v[116:117], v[116:117], 0, s[10:11]
	s_waitcnt lgkmcnt(0)
	v_add_f32_e32 v114, v114, v115
	global_store_dword v[116:117], v114, off
.LBB0_672:
	s_or_b64 exec, exec, s[30:31]
	v_or_b32_e32 v114, 32, v164
	s_waitcnt lgkmcnt(0)
	v_ashrrev_i32_e32 v115, 31, v114
	v_lshlrev_b64 v[116:117], 11, v[114:115]
	v_lshl_add_u64 v[116:117], s[20:21], 0, v[116:117]
	v_lshl_add_u64 v[124:125], v[162:163], 1, v[116:117]
	s_nop 1
	v_pk_mov_b32 v[116:117], v[202:203], v[202:203] op_sel:[0,1]
	v_pk_mov_b32 v[118:119], v[204:205], v[204:205] op_sel:[0,1]
	v_pk_mov_b32 v[120:121], v[206:207], v[206:207] op_sel:[0,1]
	v_pk_mov_b32 v[122:123], v[208:209], v[208:209] op_sel:[0,1]
	v_pk_add_f32 v[112:113], v[112:113], 0 op_sel_hi:[1,0]
	v_pk_add_f32 v[110:111], v[110:111], 0 op_sel_hi:[1,0]
	v_pk_add_f32 v[108:109], v[108:109], 0 op_sel_hi:[1,0]
	v_pk_add_f32 v[106:107], v[106:107], 0 op_sel_hi:[1,0]
	v_pk_add_f32 v[104:105], v[104:105], 0 op_sel_hi:[1,0]
	v_pk_add_f32 v[102:103], v[102:103], 0 op_sel_hi:[1,0]
	v_pk_add_f32 v[100:101], v[100:101], 0 op_sel_hi:[1,0]
	v_pk_add_f32 v[98:99], v[98:99], 0 op_sel_hi:[1,0]
	v_lshlrev_b32_e32 v126, 16, v116
	v_and_b32_e32 v127, 0xffff0000, v116
	v_lshlrev_b32_e32 v116, 16, v117
	v_and_b32_e32 v117, 0xffff0000, v117
	v_lshlrev_b32_e32 v128, 16, v118
	v_and_b32_e32 v129, 0xffff0000, v118
	v_lshlrev_b32_e32 v118, 16, v119
	v_and_b32_e32 v119, 0xffff0000, v119
	v_lshlrev_b32_e32 v130, 16, v120
	v_and_b32_e32 v131, 0xffff0000, v120
	v_lshlrev_b32_e32 v120, 16, v121
	v_and_b32_e32 v121, 0xffff0000, v121
	v_lshlrev_b32_e32 v134, 16, v122
	v_and_b32_e32 v135, 0xffff0000, v122
	v_lshlrev_b32_e32 v122, 16, v123
	v_and_b32_e32 v123, 0xffff0000, v123
	v_pk_fma_f32 v[112:113], v[112:113], v[96:97], v[116:117]
	v_pk_fma_f32 v[110:111], v[110:111], v[94:95], v[126:127]
	v_pk_fma_f32 v[108:109], v[108:109], v[92:93], v[118:119]
	v_pk_fma_f32 v[106:107], v[106:107], v[90:91], v[128:129]
	v_pk_fma_f32 v[104:105], v[104:105], v[88:89], v[120:121]
	v_pk_fma_f32 v[102:103], v[102:103], v[86:87], v[130:131]
	v_pk_fma_f32 v[116:117], v[100:101], v[84:85], v[122:123]
	v_pk_fma_f32 v[118:119], v[98:99], v[82:83], v[134:135]
	v_mul_f32_e32 v100, v111, v111
	v_mul_f32_e32 v101, v113, v113
	v_mul_f32_e32 v120, v107, v107
	v_mul_f32_e32 v121, v109, v109
	v_cvt_pk_bf16_f32 v98, v110, v111
	v_cvt_pk_bf16_f32 v99, v112, v113
	v_mul_f32_e32 v111, v103, v103
	v_mul_f32_e32 v113, v105, v105
	v_mul_f32_e32 v122, v119, v119
	v_mul_f32_e32 v123, v117, v117
	v_fmac_f32_e32 v100, v110, v110
	v_fmac_f32_e32 v101, v112, v112
	v_fmac_f32_e32 v120, v106, v106
	v_fmac_f32_e32 v121, v108, v108
	v_fmac_f32_e32 v111, v102, v102
	v_fmac_f32_e32 v113, v104, v104
	v_fmac_f32_e32 v122, v118, v118
	v_fmac_f32_e32 v123, v116, v116
	v_add_f32_e32 v100, v100, v101
	v_add_f32_e32 v101, v120, v121
	v_add_f32_e32 v110, v111, v113
	v_add_f32_e32 v111, v122, v123
	v_add_f32_e32 v100, v100, v101
	v_add_f32_e32 v101, v110, v111
	v_add_f32_e32 v110, v100, v101
	ds_bpermute_b32 v111, v132, v110
	v_cvt_pk_bf16_f32 v100, v106, v107
	v_cvt_pk_bf16_f32 v101, v108, v109
	global_store_dwordx4 v[124:125], v[98:101], off
	s_waitcnt lgkmcnt(0)
	s_nop 0
	v_add_f32_e32 v98, v110, v111
	ds_bpermute_b32 v99, v133, v98
	v_cvt_pk_bf16_f32 v100, v102, v103
	v_cvt_pk_bf16_f32 v101, v104, v105
	v_cvt_pk_bf16_f32 v102, v118, v119
	v_cvt_pk_bf16_f32 v103, v116, v117
	global_store_dwordx4 v[124:125], v[100:103], off offset:256
	s_and_saveexec_b64 s[30:31], s[0:1]
	s_cbranch_execz .LBB0_674
	v_lshlrev_b64 v[100:101], 6, v[114:115]
	v_lshl_add_u64 v[100:101], s[14:15], 0, v[100:101]
	v_lshl_add_u64 v[100:101], s[28:29], 2, v[100:101]
	s_lshl_b32 s10, s62, 2
	v_lshl_add_u64 v[100:101], v[100:101], 0, s[10:11]
	s_waitcnt lgkmcnt(0)
	v_add_f32_e32 v98, v98, v99
	global_store_dword v[100:101], v98, off
.LBB0_674:
	s_or_b64 exec, exec, s[30:31]
	v_or_b32_e32 v98, 48, v164
	s_waitcnt lgkmcnt(0)
	v_ashrrev_i32_e32 v99, 31, v98
	v_lshlrev_b64 v[100:101], 11, v[98:99]
	v_lshl_add_u64 v[100:101], s[20:21], 0, v[100:101]
	v_lshl_add_u64 v[108:109], v[162:163], 1, v[100:101]
	s_nop 1
	v_pk_mov_b32 v[100:101], v[212:213], v[212:213] op_sel:[0,1]
	v_pk_mov_b32 v[102:103], v[214:215], v[214:215] op_sel:[0,1]
	v_pk_mov_b32 v[104:105], v[216:217], v[216:217] op_sel:[0,1]
	v_pk_mov_b32 v[106:107], v[218:219], v[218:219] op_sel:[0,1]
	v_pk_add_f32 v[80:81], v[80:81], 0 op_sel_hi:[1,0]
	v_pk_add_f32 v[78:79], v[78:79], 0 op_sel_hi:[1,0]
	v_pk_add_f32 v[76:77], v[76:77], 0 op_sel_hi:[1,0]
	v_pk_add_f32 v[74:75], v[74:75], 0 op_sel_hi:[1,0]
	v_pk_add_f32 v[72:73], v[72:73], 0 op_sel_hi:[1,0]
	v_pk_add_f32 v[70:71], v[70:71], 0 op_sel_hi:[1,0]
	v_pk_add_f32 v[68:69], v[68:69], 0 op_sel_hi:[1,0]
	v_pk_add_f32 v[66:67], v[66:67], 0 op_sel_hi:[1,0]
	v_lshlrev_b32_e32 v110, 16, v100
	v_and_b32_e32 v111, 0xffff0000, v100
	v_lshlrev_b32_e32 v100, 16, v101
	v_and_b32_e32 v101, 0xffff0000, v101
	v_lshlrev_b32_e32 v112, 16, v102
	v_and_b32_e32 v113, 0xffff0000, v102
	v_lshlrev_b32_e32 v102, 16, v103
	v_and_b32_e32 v103, 0xffff0000, v103
	v_lshlrev_b32_e32 v114, 16, v104
	v_and_b32_e32 v115, 0xffff0000, v104
	v_lshlrev_b32_e32 v104, 16, v105
	v_and_b32_e32 v105, 0xffff0000, v105
	v_lshlrev_b32_e32 v116, 16, v106
	v_and_b32_e32 v117, 0xffff0000, v106
	v_lshlrev_b32_e32 v106, 16, v107
	v_and_b32_e32 v107, 0xffff0000, v107
	v_pk_fma_f32 v[80:81], v[80:81], v[96:97], v[100:101]
	v_pk_fma_f32 v[78:79], v[78:79], v[94:95], v[110:111]
	v_pk_fma_f32 v[76:77], v[76:77], v[92:93], v[102:103]
	v_pk_fma_f32 v[74:75], v[74:75], v[90:91], v[112:113]
	v_pk_fma_f32 v[72:73], v[72:73], v[88:89], v[104:105]
	v_pk_fma_f32 v[70:71], v[70:71], v[86:87], v[114:115]
	v_pk_fma_f32 v[100:101], v[68:69], v[84:85], v[106:107]
	v_pk_fma_f32 v[102:103], v[66:67], v[82:83], v[116:117]
	v_mul_f32_e32 v68, v79, v79
	v_mul_f32_e32 v69, v81, v81
	v_mul_f32_e32 v104, v75, v75
	v_mul_f32_e32 v105, v77, v77
	v_cvt_pk_bf16_f32 v66, v78, v79
	v_cvt_pk_bf16_f32 v67, v80, v81
	v_mul_f32_e32 v79, v71, v71
	v_mul_f32_e32 v81, v73, v73
	v_mul_f32_e32 v106, v103, v103
	v_mul_f32_e32 v107, v101, v101
	v_fmac_f32_e32 v68, v78, v78
	v_fmac_f32_e32 v69, v80, v80
	v_fmac_f32_e32 v104, v74, v74
	v_fmac_f32_e32 v105, v76, v76
	v_fmac_f32_e32 v79, v70, v70
	v_fmac_f32_e32 v81, v72, v72
	v_fmac_f32_e32 v106, v102, v102
	v_fmac_f32_e32 v107, v100, v100
	v_add_f32_e32 v68, v68, v69
	v_add_f32_e32 v69, v104, v105
	v_add_f32_e32 v78, v79, v81
	v_add_f32_e32 v79, v106, v107
	v_add_f32_e32 v68, v68, v69
	v_add_f32_e32 v69, v78, v79
	v_add_f32_e32 v78, v68, v69
	ds_bpermute_b32 v79, v132, v78
	v_cvt_pk_bf16_f32 v68, v74, v75
	v_cvt_pk_bf16_f32 v69, v76, v77
	global_store_dwordx4 v[108:109], v[66:69], off
	s_waitcnt lgkmcnt(0)
	s_nop 0
	v_add_f32_e32 v66, v78, v79
	ds_bpermute_b32 v67, v133, v66
	v_cvt_pk_bf16_f32 v68, v70, v71
	v_cvt_pk_bf16_f32 v69, v72, v73
	v_cvt_pk_bf16_f32 v70, v102, v103
	v_cvt_pk_bf16_f32 v71, v100, v101
	global_store_dwordx4 v[108:109], v[68:71], off offset:256
	s_and_saveexec_b64 s[30:31], s[0:1]
	s_cbranch_execz .LBB0_676
	v_lshlrev_b64 v[68:69], 6, v[98:99]
	v_lshl_add_u64 v[68:69], s[14:15], 0, v[68:69]
	v_lshl_add_u64 v[68:69], s[28:29], 2, v[68:69]
	s_lshl_b32 s10, s62, 2
	v_lshl_add_u64 v[68:69], v[68:69], 0, s[10:11]
	s_waitcnt lgkmcnt(0)
	v_add_f32_e32 v66, v66, v67
	global_store_dword v[68:69], v66, off
.LBB0_676:
	s_or_b64 exec, exec, s[30:31]
	v_add_u32_e32 v66, 0x80, v164
	s_waitcnt lgkmcnt(0)
	v_ashrrev_i32_e32 v67, 31, v66
	v_lshlrev_b64 v[68:69], 11, v[66:67]
	v_lshl_add_u64 v[68:69], s[20:21], 0, v[68:69]
	v_lshl_add_u64 v[76:77], v[162:163], 1, v[68:69]
	s_nop 1
	v_pk_mov_b32 v[68:69], v[220:221], v[220:221] op_sel:[0,1]
	v_pk_mov_b32 v[70:71], v[222:223], v[222:223] op_sel:[0,1]
	v_pk_mov_b32 v[72:73], v[224:225], v[224:225] op_sel:[0,1]
	v_pk_mov_b32 v[74:75], v[226:227], v[226:227] op_sel:[0,1]
	v_pk_add_f32 v[64:65], v[64:65], 0 op_sel_hi:[1,0]
	v_pk_add_f32 v[62:63], v[62:63], 0 op_sel_hi:[1,0]
	v_pk_add_f32 v[60:61], v[60:61], 0 op_sel_hi:[1,0]
	v_pk_add_f32 v[58:59], v[58:59], 0 op_sel_hi:[1,0]
	v_pk_add_f32 v[56:57], v[56:57], 0 op_sel_hi:[1,0]
	v_pk_add_f32 v[54:55], v[54:55], 0 op_sel_hi:[1,0]
	v_pk_add_f32 v[52:53], v[52:53], 0 op_sel_hi:[1,0]
	v_pk_add_f32 v[50:51], v[50:51], 0 op_sel_hi:[1,0]
	v_lshlrev_b32_e32 v78, 16, v68
	v_and_b32_e32 v79, 0xffff0000, v68
	v_lshlrev_b32_e32 v68, 16, v69
	v_and_b32_e32 v69, 0xffff0000, v69
	v_lshlrev_b32_e32 v80, 16, v70
	v_and_b32_e32 v81, 0xffff0000, v70
	v_lshlrev_b32_e32 v70, 16, v71
	v_and_b32_e32 v71, 0xffff0000, v71
	v_lshlrev_b32_e32 v98, 16, v72
	v_and_b32_e32 v99, 0xffff0000, v72
	v_lshlrev_b32_e32 v72, 16, v73
	v_and_b32_e32 v73, 0xffff0000, v73
	v_lshlrev_b32_e32 v100, 16, v74
	v_and_b32_e32 v101, 0xffff0000, v74
	v_lshlrev_b32_e32 v74, 16, v75
	v_and_b32_e32 v75, 0xffff0000, v75
	v_pk_fma_f32 v[64:65], v[64:65], v[96:97], v[68:69]
	v_pk_fma_f32 v[62:63], v[62:63], v[94:95], v[78:79]
	v_pk_fma_f32 v[60:61], v[60:61], v[92:93], v[70:71]
	v_pk_fma_f32 v[58:59], v[58:59], v[90:91], v[80:81]
	v_pk_fma_f32 v[56:57], v[56:57], v[88:89], v[72:73]
	v_pk_fma_f32 v[54:55], v[54:55], v[86:87], v[98:99]
	v_pk_fma_f32 v[68:69], v[52:53], v[84:85], v[74:75]
	v_pk_fma_f32 v[70:71], v[50:51], v[82:83], v[100:101]
	v_mul_f32_e32 v52, v63, v63
	v_mul_f32_e32 v53, v65, v65
	v_mul_f32_e32 v72, v59, v59
	v_mul_f32_e32 v73, v61, v61
	v_cvt_pk_bf16_f32 v50, v62, v63
	v_cvt_pk_bf16_f32 v51, v64, v65
	v_mul_f32_e32 v63, v55, v55
	v_mul_f32_e32 v65, v57, v57
	v_mul_f32_e32 v74, v71, v71
	v_mul_f32_e32 v75, v69, v69
	v_fmac_f32_e32 v52, v62, v62
	v_fmac_f32_e32 v53, v64, v64
	v_fmac_f32_e32 v72, v58, v58
	v_fmac_f32_e32 v73, v60, v60
	v_fmac_f32_e32 v63, v54, v54
	v_fmac_f32_e32 v65, v56, v56
	v_fmac_f32_e32 v74, v70, v70
	v_fmac_f32_e32 v75, v68, v68
	v_add_f32_e32 v52, v52, v53
	v_add_f32_e32 v53, v72, v73
	v_add_f32_e32 v62, v63, v65
	v_add_f32_e32 v63, v74, v75
	v_add_f32_e32 v52, v52, v53
	v_add_f32_e32 v53, v62, v63
	v_add_f32_e32 v62, v52, v53
	ds_bpermute_b32 v63, v132, v62
	v_cvt_pk_bf16_f32 v52, v58, v59
	v_cvt_pk_bf16_f32 v53, v60, v61
	global_store_dwordx4 v[76:77], v[50:53], off
	s_waitcnt lgkmcnt(0)
	s_nop 0
	v_add_f32_e32 v50, v62, v63
	ds_bpermute_b32 v51, v133, v50
	v_cvt_pk_bf16_f32 v52, v54, v55
	v_cvt_pk_bf16_f32 v53, v56, v57
	v_cvt_pk_bf16_f32 v54, v70, v71
	v_cvt_pk_bf16_f32 v55, v68, v69
	global_store_dwordx4 v[76:77], v[52:55], off offset:256
	s_and_saveexec_b64 s[30:31], s[0:1]
	s_cbranch_execz .LBB0_678
	v_lshlrev_b64 v[52:53], 6, v[66:67]
	v_lshl_add_u64 v[52:53], s[14:15], 0, v[52:53]
	v_lshl_add_u64 v[52:53], s[28:29], 2, v[52:53]
	s_lshl_b32 s10, s62, 2
	v_lshl_add_u64 v[52:53], v[52:53], 0, s[10:11]
	s_waitcnt lgkmcnt(0)
	v_add_f32_e32 v50, v50, v51
	global_store_dword v[52:53], v50, off
.LBB0_678:
	s_or_b64 exec, exec, s[30:31]
	v_add_u32_e32 v50, 0x90, v164
	s_waitcnt lgkmcnt(0)
	v_ashrrev_i32_e32 v51, 31, v50
	v_lshlrev_b64 v[52:53], 11, v[50:51]
	v_lshl_add_u64 v[52:53], s[20:21], 0, v[52:53]
	v_lshl_add_u64 v[60:61], v[162:163], 1, v[52:53]
	s_nop 1
	v_pk_mov_b32 v[52:53], v[228:229], v[228:229] op_sel:[0,1]
	v_pk_mov_b32 v[54:55], v[230:231], v[230:231] op_sel:[0,1]
	v_pk_mov_b32 v[56:57], v[232:233], v[232:233] op_sel:[0,1]
	v_pk_mov_b32 v[58:59], v[234:235], v[234:235] op_sel:[0,1]
	v_pk_add_f32 v[48:49], v[48:49], 0 op_sel_hi:[1,0]
	v_pk_add_f32 v[46:47], v[46:47], 0 op_sel_hi:[1,0]
	v_pk_add_f32 v[44:45], v[44:45], 0 op_sel_hi:[1,0]
	v_pk_add_f32 v[42:43], v[42:43], 0 op_sel_hi:[1,0]
	v_pk_add_f32 v[40:41], v[40:41], 0 op_sel_hi:[1,0]
	v_pk_add_f32 v[38:39], v[38:39], 0 op_sel_hi:[1,0]
	v_pk_add_f32 v[36:37], v[36:37], 0 op_sel_hi:[1,0]
	v_pk_add_f32 v[34:35], v[34:35], 0 op_sel_hi:[1,0]
	v_lshlrev_b32_e32 v62, 16, v52
	v_and_b32_e32 v63, 0xffff0000, v52
	v_lshlrev_b32_e32 v52, 16, v53
	v_and_b32_e32 v53, 0xffff0000, v53
	v_lshlrev_b32_e32 v64, 16, v54
	v_and_b32_e32 v65, 0xffff0000, v54
	v_lshlrev_b32_e32 v54, 16, v55
	v_and_b32_e32 v55, 0xffff0000, v55
	v_lshlrev_b32_e32 v66, 16, v56
	v_and_b32_e32 v67, 0xffff0000, v56
	v_lshlrev_b32_e32 v56, 16, v57
	v_and_b32_e32 v57, 0xffff0000, v57
	v_lshlrev_b32_e32 v68, 16, v58
	v_and_b32_e32 v69, 0xffff0000, v58
	v_lshlrev_b32_e32 v58, 16, v59
	v_and_b32_e32 v59, 0xffff0000, v59
	v_pk_fma_f32 v[48:49], v[48:49], v[96:97], v[52:53]
	v_pk_fma_f32 v[46:47], v[46:47], v[94:95], v[62:63]
	v_pk_fma_f32 v[44:45], v[44:45], v[92:93], v[54:55]
	v_pk_fma_f32 v[42:43], v[42:43], v[90:91], v[64:65]
	v_pk_fma_f32 v[40:41], v[40:41], v[88:89], v[56:57]
	v_pk_fma_f32 v[38:39], v[38:39], v[86:87], v[66:67]
	v_pk_fma_f32 v[52:53], v[36:37], v[84:85], v[58:59]
	v_pk_fma_f32 v[54:55], v[34:35], v[82:83], v[68:69]
	v_mul_f32_e32 v36, v47, v47
	v_mul_f32_e32 v37, v49, v49
	v_mul_f32_e32 v56, v43, v43
	v_mul_f32_e32 v57, v45, v45
	v_cvt_pk_bf16_f32 v34, v46, v47
	v_cvt_pk_bf16_f32 v35, v48, v49
	v_mul_f32_e32 v47, v39, v39
	v_mul_f32_e32 v49, v41, v41
	v_mul_f32_e32 v58, v55, v55
	v_mul_f32_e32 v59, v53, v53
	v_fmac_f32_e32 v36, v46, v46
	v_fmac_f32_e32 v37, v48, v48
	v_fmac_f32_e32 v56, v42, v42
	v_fmac_f32_e32 v57, v44, v44
	v_fmac_f32_e32 v47, v38, v38
	v_fmac_f32_e32 v49, v40, v40
	v_fmac_f32_e32 v58, v54, v54
	v_fmac_f32_e32 v59, v52, v52
	v_add_f32_e32 v36, v36, v37
	v_add_f32_e32 v37, v56, v57
	v_add_f32_e32 v46, v47, v49
	v_add_f32_e32 v47, v58, v59
	v_add_f32_e32 v36, v36, v37
	v_add_f32_e32 v37, v46, v47
	v_add_f32_e32 v46, v36, v37
	ds_bpermute_b32 v47, v132, v46
	v_cvt_pk_bf16_f32 v36, v42, v43
	v_cvt_pk_bf16_f32 v37, v44, v45
	global_store_dwordx4 v[60:61], v[34:37], off
	s_waitcnt lgkmcnt(0)
	s_nop 0
	v_add_f32_e32 v34, v46, v47
	ds_bpermute_b32 v35, v133, v34
	v_cvt_pk_bf16_f32 v36, v38, v39
	v_cvt_pk_bf16_f32 v37, v40, v41
	v_cvt_pk_bf16_f32 v38, v54, v55
	v_cvt_pk_bf16_f32 v39, v52, v53
	global_store_dwordx4 v[60:61], v[36:39], off offset:256
	s_and_saveexec_b64 s[30:31], s[0:1]
	s_cbranch_execz .LBB0_680
	v_lshlrev_b64 v[36:37], 6, v[50:51]
	v_lshl_add_u64 v[36:37], s[14:15], 0, v[36:37]
	v_lshl_add_u64 v[36:37], s[28:29], 2, v[36:37]
	s_lshl_b32 s10, s62, 2
	v_lshl_add_u64 v[36:37], v[36:37], 0, s[10:11]
	s_waitcnt lgkmcnt(0)
	v_add_f32_e32 v34, v34, v35
	global_store_dword v[36:37], v34, off
.LBB0_680:
	s_or_b64 exec, exec, s[30:31]
	v_add_u32_e32 v34, 0xa0, v164
	s_waitcnt lgkmcnt(0)
	v_ashrrev_i32_e32 v35, 31, v34
	v_lshlrev_b64 v[36:37], 11, v[34:35]
	v_lshl_add_u64 v[36:37], s[20:21], 0, v[36:37]
	v_lshl_add_u64 v[44:45], v[162:163], 1, v[36:37]
	s_nop 1
	v_pk_mov_b32 v[36:37], v[236:237], v[236:237] op_sel:[0,1]
	v_pk_mov_b32 v[38:39], v[238:239], v[238:239] op_sel:[0,1]
	v_pk_mov_b32 v[40:41], v[240:241], v[240:241] op_sel:[0,1]
	v_pk_mov_b32 v[42:43], v[242:243], v[242:243] op_sel:[0,1]
	v_pk_add_f32 v[32:33], v[32:33], 0 op_sel_hi:[1,0]
	v_pk_add_f32 v[30:31], v[30:31], 0 op_sel_hi:[1,0]
	v_pk_add_f32 v[28:29], v[28:29], 0 op_sel_hi:[1,0]
	v_pk_add_f32 v[26:27], v[26:27], 0 op_sel_hi:[1,0]
	v_pk_add_f32 v[24:25], v[24:25], 0 op_sel_hi:[1,0]
	v_pk_add_f32 v[22:23], v[22:23], 0 op_sel_hi:[1,0]
	v_pk_add_f32 v[20:21], v[20:21], 0 op_sel_hi:[1,0]
	v_pk_add_f32 v[18:19], v[18:19], 0 op_sel_hi:[1,0]
	v_lshlrev_b32_e32 v46, 16, v36
	v_and_b32_e32 v47, 0xffff0000, v36
	v_lshlrev_b32_e32 v36, 16, v37
	v_and_b32_e32 v37, 0xffff0000, v37
	v_lshlrev_b32_e32 v48, 16, v38
	v_and_b32_e32 v49, 0xffff0000, v38
	v_lshlrev_b32_e32 v38, 16, v39
	v_and_b32_e32 v39, 0xffff0000, v39
	v_lshlrev_b32_e32 v50, 16, v40
	v_and_b32_e32 v51, 0xffff0000, v40
	v_lshlrev_b32_e32 v40, 16, v41
	v_and_b32_e32 v41, 0xffff0000, v41
	v_lshlrev_b32_e32 v52, 16, v42
	v_and_b32_e32 v53, 0xffff0000, v42
	v_lshlrev_b32_e32 v42, 16, v43
	v_and_b32_e32 v43, 0xffff0000, v43
	v_pk_fma_f32 v[32:33], v[32:33], v[96:97], v[36:37]
	v_pk_fma_f32 v[30:31], v[30:31], v[94:95], v[46:47]
	v_pk_fma_f32 v[28:29], v[28:29], v[92:93], v[38:39]
	v_pk_fma_f32 v[26:27], v[26:27], v[90:91], v[48:49]
	v_pk_fma_f32 v[24:25], v[24:25], v[88:89], v[40:41]
	v_pk_fma_f32 v[22:23], v[22:23], v[86:87], v[50:51]
	v_pk_fma_f32 v[36:37], v[20:21], v[84:85], v[42:43]
	v_pk_fma_f32 v[38:39], v[18:19], v[82:83], v[52:53]
	v_mul_f32_e32 v20, v31, v31
	v_mul_f32_e32 v21, v33, v33
	v_mul_f32_e32 v40, v27, v27
	v_mul_f32_e32 v41, v29, v29
	v_cvt_pk_bf16_f32 v18, v30, v31
	v_cvt_pk_bf16_f32 v19, v32, v33
	v_mul_f32_e32 v31, v23, v23
	v_mul_f32_e32 v33, v25, v25
	v_mul_f32_e32 v42, v39, v39
	v_mul_f32_e32 v43, v37, v37
	v_fmac_f32_e32 v20, v30, v30
	v_fmac_f32_e32 v21, v32, v32
	v_fmac_f32_e32 v40, v26, v26
	v_fmac_f32_e32 v41, v28, v28
	v_fmac_f32_e32 v31, v22, v22
	v_fmac_f32_e32 v33, v24, v24
	v_fmac_f32_e32 v42, v38, v38
	v_fmac_f32_e32 v43, v36, v36
	v_add_f32_e32 v20, v20, v21
	v_add_f32_e32 v21, v40, v41
	v_add_f32_e32 v30, v31, v33
	v_add_f32_e32 v31, v42, v43
	v_add_f32_e32 v20, v20, v21
	v_add_f32_e32 v21, v30, v31
	v_add_f32_e32 v30, v20, v21
	ds_bpermute_b32 v31, v132, v30
	v_cvt_pk_bf16_f32 v20, v26, v27
	v_cvt_pk_bf16_f32 v21, v28, v29
	global_store_dwordx4 v[44:45], v[18:21], off
	s_waitcnt lgkmcnt(0)
	s_nop 0
	v_add_f32_e32 v18, v30, v31
	ds_bpermute_b32 v19, v133, v18
	v_cvt_pk_bf16_f32 v20, v22, v23
	v_cvt_pk_bf16_f32 v21, v24, v25
	v_cvt_pk_bf16_f32 v22, v38, v39
	v_cvt_pk_bf16_f32 v23, v36, v37
	global_store_dwordx4 v[44:45], v[20:23], off offset:256
	s_and_saveexec_b64 s[30:31], s[0:1]
	s_cbranch_execz .LBB0_682
	v_lshlrev_b64 v[20:21], 6, v[34:35]
	v_lshl_add_u64 v[20:21], s[14:15], 0, v[20:21]
	v_lshl_add_u64 v[20:21], s[28:29], 2, v[20:21]
	s_lshl_b32 s10, s62, 2
	v_lshl_add_u64 v[20:21], v[20:21], 0, s[10:11]
	s_waitcnt lgkmcnt(0)
	v_add_f32_e32 v18, v18, v19
	global_store_dword v[20:21], v18, off
.LBB0_682:
	s_or_b64 exec, exec, s[30:31]
	v_add_u32_e32 v18, 0xb0, v164
	s_waitcnt lgkmcnt(0)
	v_ashrrev_i32_e32 v19, 31, v18
	v_lshlrev_b64 v[20:21], 11, v[18:19]
	v_lshl_add_u64 v[20:21], s[20:21], 0, v[20:21]
	v_lshl_add_u64 v[28:29], v[162:163], 1, v[20:21]
	s_nop 1
	v_pk_mov_b32 v[20:21], v[244:245], v[244:245] op_sel:[0,1]
	v_pk_mov_b32 v[22:23], v[246:247], v[246:247] op_sel:[0,1]
	v_pk_mov_b32 v[24:25], v[248:249], v[248:249] op_sel:[0,1]
	v_pk_mov_b32 v[26:27], v[250:251], v[250:251] op_sel:[0,1]
	v_pk_add_f32 v[16:17], v[16:17], 0 op_sel_hi:[1,0]
	v_pk_add_f32 v[14:15], v[14:15], 0 op_sel_hi:[1,0]
	v_pk_add_f32 v[12:13], v[12:13], 0 op_sel_hi:[1,0]
	v_pk_add_f32 v[10:11], v[10:11], 0 op_sel_hi:[1,0]
	v_pk_add_f32 v[8:9], v[8:9], 0 op_sel_hi:[1,0]
	v_pk_add_f32 v[6:7], v[6:7], 0 op_sel_hi:[1,0]
	v_pk_add_f32 v[4:5], v[4:5], 0 op_sel_hi:[1,0]
	v_pk_add_f32 v[2:3], v[2:3], 0 op_sel_hi:[1,0]
	v_lshlrev_b32_e32 v30, 16, v20
	v_and_b32_e32 v31, 0xffff0000, v20
	v_lshlrev_b32_e32 v20, 16, v21
	v_and_b32_e32 v21, 0xffff0000, v21
	v_lshlrev_b32_e32 v32, 16, v22
	v_and_b32_e32 v33, 0xffff0000, v22
	v_lshlrev_b32_e32 v22, 16, v23
	v_and_b32_e32 v23, 0xffff0000, v23
	v_lshlrev_b32_e32 v34, 16, v24
	v_and_b32_e32 v35, 0xffff0000, v24
	v_lshlrev_b32_e32 v24, 16, v25
	v_and_b32_e32 v25, 0xffff0000, v25
	v_lshlrev_b32_e32 v36, 16, v26
	v_and_b32_e32 v37, 0xffff0000, v26
	v_lshlrev_b32_e32 v26, 16, v27
	v_and_b32_e32 v27, 0xffff0000, v27
	v_pk_fma_f32 v[16:17], v[16:17], v[96:97], v[20:21]
	v_pk_fma_f32 v[14:15], v[14:15], v[94:95], v[30:31]
	v_pk_fma_f32 v[12:13], v[12:13], v[92:93], v[22:23]
	v_pk_fma_f32 v[10:11], v[10:11], v[90:91], v[32:33]
	v_pk_fma_f32 v[8:9], v[8:9], v[88:89], v[24:25]
	v_pk_fma_f32 v[6:7], v[6:7], v[86:87], v[34:35]
	v_pk_fma_f32 v[20:21], v[4:5], v[84:85], v[26:27]
	v_pk_fma_f32 v[22:23], v[2:3], v[82:83], v[36:37]
	v_mul_f32_e32 v4, v15, v15
	v_mul_f32_e32 v5, v17, v17
	v_mul_f32_e32 v24, v11, v11
	v_mul_f32_e32 v25, v13, v13
	v_cvt_pk_bf16_f32 v2, v14, v15
	v_cvt_pk_bf16_f32 v3, v16, v17
	v_mul_f32_e32 v15, v7, v7
	v_mul_f32_e32 v17, v9, v9
	v_mul_f32_e32 v26, v23, v23
	v_mul_f32_e32 v27, v21, v21
	v_fmac_f32_e32 v4, v14, v14
	v_fmac_f32_e32 v5, v16, v16
	v_fmac_f32_e32 v24, v10, v10
	v_fmac_f32_e32 v25, v12, v12
	v_fmac_f32_e32 v15, v6, v6
	v_fmac_f32_e32 v17, v8, v8
	v_fmac_f32_e32 v26, v22, v22
	v_fmac_f32_e32 v27, v20, v20
	v_add_f32_e32 v4, v4, v5
	v_add_f32_e32 v5, v24, v25
	v_add_f32_e32 v14, v15, v17
	v_add_f32_e32 v15, v26, v27
	v_add_f32_e32 v4, v4, v5
	v_add_f32_e32 v5, v14, v15
	v_add_f32_e32 v14, v4, v5
	ds_bpermute_b32 v15, v132, v14
	v_cvt_pk_bf16_f32 v4, v10, v11
	v_cvt_pk_bf16_f32 v5, v12, v13
	global_store_dwordx4 v[28:29], v[2:5], off
	s_waitcnt lgkmcnt(0)
	s_nop 0
	v_add_f32_e32 v2, v14, v15
	ds_bpermute_b32 v3, v133, v2
	v_cvt_pk_bf16_f32 v4, v6, v7
	v_cvt_pk_bf16_f32 v5, v8, v9
	v_cvt_pk_bf16_f32 v6, v22, v23
	v_cvt_pk_bf16_f32 v7, v20, v21
	global_store_dwordx4 v[28:29], v[4:7], off offset:256
	s_and_saveexec_b64 s[30:31], s[0:1]
	s_cbranch_execz .LBB0_684
	v_lshlrev_b64 v[4:5], 6, v[18:19]
	v_lshl_add_u64 v[4:5], s[14:15], 0, v[4:5]
	v_lshl_add_u64 v[4:5], s[28:29], 2, v[4:5]
	s_lshl_b32 s10, s62, 2
	v_lshl_add_u64 v[4:5], v[4:5], 0, s[10:11]
	s_waitcnt lgkmcnt(0)
	v_add_f32_e32 v2, v2, v3
	global_store_dword v[4:5], v2, off
